# speedup vs baseline: 1.0362x; 1.0031x over previous
; DEV void phase_attn(const Params& p, unsigned char* smem) {
;     ...
; #pragma unroll
;       for (int kf = 0; kf < 2; ++kf) {
;         const int krow = 8 * (fr >> 2) + 4 * kf + (fr & 3);
;         bf16x8 Ak0 = *reinterpret_cast<const bf16x8*>(sKt + krow * 144 + fq * 16);
;         bf16x8 Ak1 = *reinterpret_cast<const bf16x8*>(sKt + krow * 144 + 64 + fq * 16);
; #pragma unroll
;         for (int qf = 0; qf < 2; ++qf) {
;           f32x4 z = f32x4{0.f, 0.f, 0.f, 0.f};
;           z = __builtin_amdgcn_mfma_f32_16x16x32_bf16(Ak0, Bq[qf][0], z, 0, 0, 0);
;           z = __builtin_amdgcn_mfma_f32_16x16x32_bf16(Ak1, Bq[qf][1], z, 0, 0, 0);
;           st[kf][qf] = z;
;         }
;       }
;       if (loc) {
; #pragma unroll
;         for (int kf = 0; kf < 2; ++kf)
; #pragma unroll
;           for (int qf = 0; qf < 2; ++qf)
; #pragma unroll
;             for (int j = 0; j < 4; ++j) {
;               int kpos = k0 + 8 * fq + 4 * kf + j, qpos = q0 + qf * 16 + fr;
;               int dd = kpos - qpos;
;               if (dd > 128 || dd < -128) st[kf][qf][j] = -1e30f;
;             }
;       }
.LBB0_284:
	v_add3_u32 v89, s39, v126, v80
	ds_read_b128 v[56:59], v89
	ds_read_b128 v[60:63], v89 offset:64
	ds_read_b128 v[102:105], v89 offset:576
	s_cmp_ge_i32 s40, s9
	s_waitcnt lgkmcnt(2)
	v_mfma_f32_16x16x32_bf16 v[64:67], v[56:59], v[0:3], 0
	v_mfma_f32_16x16x32_bf16 v[56:59], v[56:59], v[8:11], 0
	s_waitcnt lgkmcnt(1)
	v_mfma_f32_16x16x32_bf16 v[68:71], v[60:63], v[4:7], v[64:67]
	v_mfma_f32_16x16x32_bf16 v[60:63], v[60:63], v[12:15], v[56:59]
	s_nop 4
	ds_read_b128 v[56:59], v89 offset:640
	s_waitcnt lgkmcnt(1)
	v_mfma_f32_16x16x32_bf16 v[64:67], v[102:105], v[0:3], 0
	v_mfma_f32_16x16x32_bf16 v[102:105], v[102:105], v[8:11], 0
	s_waitcnt lgkmcnt(0)
	v_mfma_f32_16x16x32_bf16 v[64:67], v[56:59], v[4:7], v[64:67]
	v_mfma_f32_16x16x32_bf16 v[56:59], v[56:59], v[12:15], v[102:105]
	s_cbranch_scc1 .LBB0_286
	s_sub_i32 s41, s9, 5
	s_lshl_b32 s41, s41, 5
	s_cmp_lg_u32 s8, 0
	s_cselect_b32 s41, 0x80, s41
	s_add_i32 s46, s41, 0x80
	s_cmp_ge_i32 s37, s46
	s_cbranch_scc1 .Lattn_mask
	s_add_i32 s41, s41, 0xffffff80
	s_cmp_le_i32 s37, s41
	s_cbranch_scc0 .LBB0_286
.Lattn_mask:
	v_add_u32_e32 v89, s37, v87
	s_nop 2
	v_add_u32_e32 v103, 0xffffff7f, v89
	v_mov_b32_e32 v102, s3
	v_cmp_gt_u32_e32 vcc, s2, v103
	v_add_u32_e32 v103, 0xffffff6f, v89
	s_nop 0
	v_cndmask_b32_e32 v68, v68, v102, vcc
	v_add_u32_e32 v102, 0xffffff80, v89
	v_cmp_lt_u32_e32 vcc, s22, v102
	v_add_u32_e32 v102, 0xffffff81, v89
	s_nop 0
	v_cndmask_b32_e32 v69, v114, v69, vcc
	v_cmp_lt_u32_e32 vcc, s22, v102
	v_add_u32_e32 v102, 0xffffff82, v89
	s_nop 0
	v_cndmask_b32_e32 v70, v114, v70, vcc
	v_cmp_lt_u32_e32 vcc, s22, v102
	v_mov_b32_e32 v102, s3
	s_nop 0
	v_cndmask_b32_e32 v71, v114, v71, vcc
	v_cmp_gt_u32_e32 vcc, s2, v103
	v_add_u32_e32 v103, 0xffffff83, v89
	s_nop 0
	v_cndmask_b32_e32 v60, v60, v102, vcc
	v_add_u32_e32 v102, 0xffffff70, v89
	v_cmp_lt_u32_e32 vcc, s22, v102
	v_add_u32_e32 v102, 0xffffff71, v89
	s_nop 0
	v_cndmask_b32_e32 v61, v114, v61, vcc
	v_cmp_lt_u32_e32 vcc, s22, v102
	v_add_u32_e32 v102, 0xffffff72, v89
	s_nop 0
	v_cndmask_b32_e32 v62, v114, v62, vcc
	v_cmp_lt_u32_e32 vcc, s22, v102
	v_mov_b32_e32 v102, s3
	s_nop 0
	v_cndmask_b32_e32 v63, v114, v63, vcc
	v_cmp_gt_u32_e32 vcc, s2, v103
	v_add_u32_e32 v103, 0xffffff73, v89
	s_nop 0
	v_cndmask_b32_e32 v64, v64, v102, vcc
	v_add_u32_e32 v102, 0xffffff84, v89
	v_cmp_lt_u32_e32 vcc, s22, v102
	v_add_u32_e32 v102, 0xffffff85, v89
	s_nop 0
	v_cndmask_b32_e32 v65, v114, v65, vcc
	v_cmp_lt_u32_e32 vcc, s22, v102
	v_add_u32_e32 v102, 0xffffff86, v89
	s_nop 0
	v_cndmask_b32_e32 v66, v114, v66, vcc
	v_cmp_lt_u32_e32 vcc, s22, v102
	v_mov_b32_e32 v102, s3
	s_nop 0
	v_cndmask_b32_e32 v67, v114, v67, vcc
	v_cmp_gt_u32_e32 vcc, s2, v103
	s_nop 1
	v_cndmask_b32_e32 v56, v56, v102, vcc
	v_add_u32_e32 v102, 0xffffff74, v89
	v_cmp_lt_u32_e32 vcc, s22, v102
	v_add_u32_e32 v102, 0xffffff75, v89
	v_add_u32_e32 v89, 0xffffff76, v89
	v_cndmask_b32_e32 v57, v114, v57, vcc
	v_cmp_lt_u32_e32 vcc, s22, v102
	s_nop 1
	v_cndmask_b32_e32 v58, v114, v58, vcc
	v_cmp_lt_u32_e32 vcc, s22, v89
	s_nop 1
	v_cndmask_b32_e32 v59, v114, v59, vcc
; DEV void phase_attn(const Params& p, unsigned char* smem) {
;     ...
;       bf16x8 bP[2];
; #pragma unroll
;       for (int qf = 0; qf < 2; ++qf) {
;         float mx = fmaxf(fmaxf(fmaxf(st[0][qf][0], st[0][qf][1]), fmaxf(st[0][qf][2], st[0][qf][3])),
;                          fmaxf(fmaxf(st[1][qf][0], st[1][qf][1]), fmaxf(st[1][qf][2], st[1][qf][3])));
;         mx = fmaxf(mx, __shfl_xor(mx, 16));
;         mx = fmaxf(mx, __shfl_xor(mx, 32));
;         float mn = fmaxf(mrun[qf], mx);
;         float al = __expf(mrun[qf] - mn);
;         mrun[qf] = mn;
;         float ps = 0.f;
;         float pv[8];
; #pragma unroll
;         for (int kf = 0; kf < 2; ++kf)
; #pragma unroll
;           for (int j = 0; j < 4; ++j) { float e = __expf(st[kf][qf][j] - mn); pv[kf * 4 + j] = e; ps += e; }
;         lpart[qf] = lpart[qf] * al + ps;
; #pragma unroll
;         for (int df = 0; df < 4; ++df) O[df][qf] *= al;
;         bf16x8 t;
; #pragma unroll
;         for (int i = 0; i < 8; ++i) t[i] = (short)f2bf(pv[i]);
;         bP[qf] = t;
;       }
; #pragma unroll
;       for (int df = 0; df < 4; ++df) {
;         bf16x8 Av = *reinterpret_cast<const bf16x8*>(sVt + (df * 16 + fr) * 80 + fq * 16);
; #pragma unroll
;         for (int qf = 0; qf < 2; ++qf) O[df][qf] = __builtin_amdgcn_mfma_f32_16x16x32_bf16(Av, bP[qf], O[df][qf], 0, 0, 0);
;       }
.LBB0_286:
	v_max_f32_e32 v89, v69, v69
	s_nop 2
	v_max_f32_e32 v102, v68, v68
	v_max_f32_e32 v89, v102, v89
	v_max_f32_e32 v102, v71, v71
	v_max_f32_e32 v103, v70, v70
	v_max_f32_e32 v102, v103, v102
	v_max_f32_e32 v103, v67, v67
	v_max_f32_e32 v104, v66, v66
	v_max_f32_e32 v103, v104, v103
	v_max3_f32 v103, v64, v65, v103
	v_max3_f32 v89, v89, v102, v103
	ds_bpermute_b32 v102, v124, v89
	s_add_i32 s37, s37, 32
	s_cmp_eq_u32 s10, s38
	s_waitcnt lgkmcnt(0)
	v_max_f32_e32 v102, v102, v102
	v_max_f32_e32 v89, v89, v102
	ds_bpermute_b32 v102, v125, v89
	s_waitcnt lgkmcnt(0)
	v_max3_f32 v89, v100, v89, v102
	v_sub_f32_e32 v65, v65, v89
	v_sub_f32_e32 v100, v100, v89
	v_sub_f32_e32 v69, v69, v89
	v_mul_f32_e32 v65, 0x3fb8aa3b, v65
	v_mul_f32_e32 v100, 0x3fb8aa3b, v100
	v_mul_f32_e32 v69, 0x3fb8aa3b, v69
	v_exp_f32_e32 v104, v65
	v_sub_f32_e32 v65, v66, v89
	v_exp_f32_e32 v108, v100
	v_exp_f32_e32 v100, v69
	v_sub_f32_e32 v69, v70, v89
	v_mul_f32_e32 v65, 0x3fb8aa3b, v65
	v_mul_f32_e32 v69, 0x3fb8aa3b, v69
	v_exp_f32_e32 v66, v65
	v_sub_f32_e32 v65, v67, v89
	v_exp_f32_e32 v70, v69
	v_sub_f32_e32 v69, v71, v89
	v_mul_f32_e32 v65, 0x3fb8aa3b, v65
	v_mul_f32_e32 v69, 0x3fb8aa3b, v69
	v_exp_f32_e32 v106, v65
	v_max_f32_e32 v65, v61, v61
	v_max_f32_e32 v67, v60, v60
	v_exp_f32_e32 v102, v69
	v_max_f32_e32 v65, v67, v65
	v_max_f32_e32 v67, v63, v63
	v_max_f32_e32 v69, v62, v62
	v_max_f32_e32 v67, v69, v67
	v_max_f32_e32 v69, v59, v59
	v_max_f32_e32 v71, v58, v58
	v_max_f32_e32 v69, v71, v69
	v_max3_f32 v69, v56, v57, v69
	v_max3_f32 v65, v65, v67, v69
	ds_bpermute_b32 v67, v124, v65
	v_sub_f32_e32 v68, v68, v89
	v_pk_mul_f32 v[42:43], v[42:43], v[108:109] op_sel_hi:[1,0]
	v_pk_mul_f32 v[40:41], v[40:41], v[108:109] op_sel_hi:[1,0]
	v_pk_mul_f32 v[46:47], v[46:47], v[108:109] op_sel_hi:[1,0]
	s_waitcnt lgkmcnt(0)
	v_max_f32_e32 v67, v67, v67
	v_max_f32_e32 v65, v65, v67
	ds_bpermute_b32 v67, v125, v65
	v_pk_mul_f32 v[44:45], v[44:45], v[108:109] op_sel_hi:[1,0]
	v_pk_mul_f32 v[50:51], v[50:51], v[108:109] op_sel_hi:[1,0]
	v_pk_mul_f32 v[48:49], v[48:49], v[108:109] op_sel_hi:[1,0]
	v_pk_mul_f32 v[54:55], v[54:55], v[108:109] op_sel_hi:[1,0]
	s_waitcnt lgkmcnt(0)
	v_max3_f32 v128, v101, v65, v67
	v_sub_f32_e32 v60, v60, v128
	v_sub_f32_e32 v65, v101, v128
	v_mul_f32_e32 v60, 0x3fb8aa3b, v60
	v_sub_f32_e32 v56, v56, v128
	v_mul_f32_e32 v65, 0x3fb8aa3b, v65
	v_exp_f32_e32 v69, v60
	v_sub_f32_e32 v60, v61, v128
	v_mul_f32_e32 v56, 0x3fb8aa3b, v56
	v_pk_mul_f32 v[52:53], v[52:53], v[108:109] op_sel_hi:[1,0]
	v_exp_f32_e32 v109, v65
	v_mul_f32_e32 v60, 0x3fb8aa3b, v60
	v_exp_f32_e32 v65, v56
	v_sub_f32_e32 v56, v57, v128
	v_mul_f32_e32 v68, 0x3fb8aa3b, v68
	v_exp_f32_e32 v101, v60
	v_sub_f32_e32 v60, v62, v128
	v_mul_f32_e32 v56, 0x3fb8aa3b, v56
	v_exp_f32_e32 v68, v68
	v_mul_f32_e32 v60, 0x3fb8aa3b, v60
	v_exp_f32_e32 v105, v56
	v_sub_f32_e32 v56, v58, v128
	v_exp_f32_e32 v71, v60
	v_sub_f32_e32 v60, v63, v128
	v_mul_f32_e32 v56, 0x3fb8aa3b, v56
	v_sub_f32_e32 v64, v64, v89
	v_mul_f32_e32 v60, 0x3fb8aa3b, v60
	v_exp_f32_e32 v67, v56
	v_sub_f32_e32 v56, v59, v128
	v_mul_f32_e32 v64, 0x3fb8aa3b, v64
	v_exp_f32_e32 v103, v60
	v_mul_f32_e32 v56, 0x3fb8aa3b, v56
	v_exp_f32_e32 v64, v64
	v_exp_f32_e32 v107, v56
	v_pk_add_f32 v[56:57], v[68:69], 0 op_sel_hi:[1,0]
	v_pk_add_f32 v[56:57], v[100:101], v[56:57]
	v_pk_add_f32 v[56:57], v[70:71], v[56:57]
	v_pk_add_f32 v[56:57], v[102:103], v[56:57]
	v_pk_add_f32 v[56:57], v[64:65], v[56:57]
	v_pk_add_f32 v[56:57], v[104:105], v[56:57]
	v_pk_add_f32 v[56:57], v[66:67], v[56:57]
	v_pk_add_f32 v[56:57], v[106:107], v[56:57]
	v_pk_fma_f32 v[96:97], v[96:97], v[108:109], v[56:57]
	v_mov_b32_e32 v56, v109
	v_pk_mul_f32 v[18:19], v[18:19], v[56:57] op_sel_hi:[1,0]
	v_pk_mul_f32 v[16:17], v[16:17], v[56:57] op_sel_hi:[1,0]
	v_pk_mul_f32 v[26:27], v[26:27], v[56:57] op_sel_hi:[1,0]
	v_pk_mul_f32 v[24:25], v[24:25], v[56:57] op_sel_hi:[1,0]
	v_pk_mul_f32 v[34:35], v[34:35], v[56:57] op_sel_hi:[1,0]
	v_pk_mul_f32 v[32:33], v[32:33], v[56:57] op_sel_hi:[1,0]
	v_pk_mul_f32 v[38:39], v[38:39], v[56:57] op_sel_hi:[1,0]
	v_pk_mul_f32 v[36:37], v[36:37], v[56:57] op_sel_hi:[1,0]
	v_cvt_pk_bf16_f32 v59, v66, v106
	v_cvt_pk_bf16_f32 v58, v64, v104
	v_cvt_pk_bf16_f32 v57, v70, v102
	v_cvt_pk_bf16_f32 v56, v68, v100
	v_add3_u32 v68, s39, v80, v127
	ds_read_b128 v[130:133], v68 offset:4608
	v_cvt_pk_bf16_f32 v63, v67, v107
	v_cvt_pk_bf16_f32 v62, v65, v105
	v_cvt_pk_bf16_f32 v61, v71, v103
	ds_read_b128 v[64:67], v68 offset:5888
	v_cvt_pk_bf16_f32 v60, v69, v101
	s_waitcnt lgkmcnt(0)
	v_mfma_f32_16x16x32_bf16 v[44:47], v[64:67], v[56:59], v[44:47]
	v_mfma_f32_16x16x32_bf16 v[24:27], v[64:67], v[60:63], v[24:27]
	ds_read_b128 v[64:67], v68 offset:7168
	s_waitcnt lgkmcnt(0)
	v_mfma_f32_16x16x32_bf16 v[48:51], v[64:67], v[56:59], v[48:51]
	v_mfma_f32_16x16x32_bf16 v[32:35], v[64:67], v[60:63], v[32:35]
	ds_read_b128 v[64:67], v68 offset:8448
	v_mfma_f32_16x16x32_bf16 v[40:43], v[130:133], v[56:59], v[40:43]
	v_mfma_f32_16x16x32_bf16 v[16:19], v[130:133], v[60:63], v[16:19]
	s_waitcnt lgkmcnt(0)
	v_mfma_f32_16x16x32_bf16 v[52:55], v[64:67], v[56:59], v[52:55]
	v_mfma_f32_16x16x32_bf16 v[36:39], v[64:67], v[60:63], v[36:39]
	s_cbranch_scc1 .LBB0_288
	s_mov_b32 s40, s38
	v_mov_b32_e32 v100, v89
	v_mov_b32_e32 v101, v128
	s_branch .LBB0_282
